# scan waves first touch every cache line their partner kv2 wave will stream (one dword per line, dead destination) to double requests in flight for the memory-K/V projection
# baseline (speedup 1.0000x reference)
.LBB0_523:
	s_add_u32 s8, s74, 0xe600000
	s_addc_u32 s9, s75, 0
	v_readlane_b32 s0, v254, 5
	s_cmpk_gt_u32 s0, 0xff
	s_waitcnt lgkmcnt(0)
	s_barrier
	s_cbranch_scc1 .LBB0_528
	v_readlane_b32 s99, v254, 25
	s_nop 3
	s_mul_i32 s99, s99, s78
	s_add_i32 s99, s99, s70
	s_and_b32 s100, s99, 0x1ff
	s_cmp_ge_u32 s99, 0x200
	s_cbranch_scc1 .Lpf_v
	s_lshr_b32 s99, s100, 5
	s_lshl_b32 s99, s99, 16
	s_add_i32 s99, s99, 0xf800000
	s_and_b32 s100, s100, 31
	s_lshl_b32 s100, s100, 16
	s_add_i32 s100, s100, 0xf00000
	s_branch .Lpf_go
.Lpf_v:
	s_lshr_b32 s99, s100, 4
	s_lshl_b32 s99, s99, 16
	s_add_i32 s99, s99, 0x1100000
	s_and_b32 s100, s100, 15
	s_lshl_b32 s100, s100, 16
	s_add_i32 s100, s100, 0xf800000
.Lpf_go:
	v_mbcnt_lo_u32_b32 v251, -1, 0
	v_mbcnt_hi_u32_b32 v251, -1, v251
	v_lshrrev_b32_e32 v252, 1, v251
	v_lshlrev_b32_e32 v252, 11, v252
	v_and_b32_e32 v251, 1, v251
	v_lshl_or_b32 v252, v251, 7, v252
	v_add_u32_e32 v251, s99, v252
	v_add_u32_e32 v252, s100, v252
	global_load_dword v253, v251, s[74:75]
	global_load_dword v253, v252, s[74:75]
	global_load_dword v253, v251, s[74:75] offset:256
	global_load_dword v253, v252, s[74:75] offset:256
	global_load_dword v253, v251, s[74:75] offset:512
	global_load_dword v253, v252, s[74:75] offset:512
	global_load_dword v253, v251, s[74:75] offset:768
	global_load_dword v253, v252, s[74:75] offset:768
	global_load_dword v253, v251, s[74:75] offset:1024
	global_load_dword v253, v252, s[74:75] offset:1024
	global_load_dword v253, v251, s[74:75] offset:1280
	global_load_dword v253, v252, s[74:75] offset:1280
	global_load_dword v253, v251, s[74:75] offset:1536
	global_load_dword v253, v252, s[74:75] offset:1536
	global_load_dword v253, v251, s[74:75] offset:1792
	global_load_dword v253, v252, s[74:75] offset:1792
	s_lshl_b32 s0, s70, 8
	v_readlane_b32 s1, v254, 44
	s_or_b32 s0, s1, s0
	v_mbcnt_lo_u32_b32 v0, -1, 0
	v_mbcnt_hi_u32_b32 v0, -1, v0
	s_mov_b32 s2, 0x10000
	v_add_u32_e32 v160, s0, v0
	v_cmp_gt_i32_e32 vcc, s2, v160
	s_and_saveexec_b64 s[4:5], vcc
	s_cbranch_execz .LBB0_527
	s_lshl_b32 s3, s78, 8
	s_mov_b64 s[12:13], 0
	s_mov_b32 s6, 0xc2fc0000
	v_mov_b32_e32 v161, 0x42800000
	v_mov_b32_e32 v1, 0
	v_not_b32_e32 v162, 63
	s_mov_b32 s7, 0x3f2aaaab
	v_mov_b32_e32 v163, 0x3ecc95a3
	s_mov_b32 s10, 0x3f317218
	v_mov_b32_e32 v164, 0x7fc00000
	v_mov_b32_e32 v165, 0xff800000
	s_mov_b32 s11, 0x33800000
	s_movk_i32 s14, 0x4000
	s_mov_b32 s15, 0x8000
	s_mov_b32 s16, 0xc000
	s_mov_b32 s17, 0x14000
	s_mov_b32 s18, 0x18000
	s_mov_b32 s19, 0x1c000
	s_mov_b32 s20, 0x20000
	s_mov_b32 s21, 0x24000
	s_mov_b32 s22, 0x28000
	s_mov_b32 s23, 0x2c000
	s_mov_b32 s24, 0x30000
	s_mov_b32 s25, 0x34000
	s_mov_b32 s26, 0x38000
	s_mov_b32 s27, 0x3c000
	s_mov_b32 s28, 0xffff
